# scan producers: redundant 44-register next=current copy at the top of each token step moved to the last-step-only path
# baseline (speedup 1.0000x reference)
; __device__ __forceinline__ void scan_unit_mfma(const TI ti, CArgs& a, int l, int u, bool ctx_out, unsigned char* ldsg) {
;     ...
;             if (e >= 0 && (e % RING) < 4 && e / RING < NCH / RING) {
;                 const int k = 4 * (e / RING) + (e % RING);
; #pragma unroll
;                 for (int i4 = 0; i4 < 4; ++i4)
; #pragma unroll
;                     for (int x = 0; x < 11; ++x) cur[i4][x] = nxt[i4][x];
;                 if (k + 1 < NSTEP) SC2_LOAD(k + 1);
.LBB0_315:
	s_andn2_b64 vcc, exec, s[6:7]
	s_cbranch_vccnz .LBB0_307
	s_and_b32 s4, s78, 0xff
	s_mul_hi_u32 s4, s4, 0x2aaaaaab
	s_lshl_b32 s4, s4, 2
	s_sub_i32 s4, s4, s36
	s_add_i32 s4, s4, s63
	s_add_i32 s5, s4, 1
	s_cmpk_gt_u32 s5, 0x5e
	s_waitcnt vmcnt(0)
	s_cbranch_scc1 .Lsc_lastmovs
	s_add_i32 s7, s4, 2
	s_lshr_b32 s4, s7, 2
	s_mul_i32 s4, s4, 6
	s_add_i32 s4, s4, s27
	s_lshl_b32 s33, s4, 4
	s_add_i32 s36, s33, 0xffffff00
	s_cmp_lt_i32 s4, 16
	s_cselect_b32 s6, 0x100, s90
	s_cselect_b32 s5, s72, s73
	s_cselect_b32 s33, s33, s36
	s_lshl_b32 s7, s7, 2
	s_and_b32 s7, s7, 12
	s_or_b32 s7, s33, s7
	s_not_b32 s33, s7
	s_add_i32 s4, s6, -1
	s_add_i32 s33, s6, s33
	s_and_b64 vcc, s[60:61], exec
	s_cselect_b32 s33, s7, s33
	s_add_i32 vcc_lo, s33, s5
	s_ashr_i32 vcc_hi, vcc_lo, 31
	s_mul_i32 s63, vcc_lo, 0x1c00
	s_mul_hi_i32 s36, vcc_lo, 0x1c00
	s_add_u32 s63, s79, s63
	s_addc_u32 s36, s81, s36
	s_add_u32 s86, s63, 0x800
	s_addc_u32 s87, s36, 0
	s_cmp_gt_i32 s33, 0
	s_cselect_b32 s63, 0xffffe400, 0
	s_cselect_b32 s36, -1, 0
	s_add_u32 s66, s86, s63
	s_addc_u32 s67, s87, s36
	s_cmp_lt_i32 s33, s4
	s_cselect_b32 s33, 0x1c00, 0
	s_add_u32 s90, s86, s33
	s_addc_u32 s91, s87, 0
	global_load_ushort v2, v22, s[66:67] offset:-2048
	global_load_ushort v4, v22, s[66:67]
	global_load_ushort v7, v22, s[66:67] offset:2048
	global_load_ushort v3, v22, s[86:87] offset:-2048
	global_load_ushort v5, v22, s[86:87]
	global_load_ushort v8, v22, s[86:87] offset:2048
	global_load_ushort v6, v22, s[90:91] offset:-2048
	global_load_ushort v9, v22, s[90:91]
	global_load_ushort v10, v22, s[90:91] offset:2048
	s_lshl_b64 s[66:67], vcc, 11
	s_add_u32 s33, s34, s66
	s_addc_u32 s36, s35, s67
	s_add_u32 s86, s33, s95
	s_addc_u32 s87, s36, 0
	s_add_u32 s33, s37, s66
	s_addc_u32 s36, s39, s67
	s_add_u32 s66, s33, s95
	s_addc_u32 s67, s36, 0
	s_xor_b32 s36, s7, -2
	s_or_b32 s33, s7, 1
	s_add_i32 s36, s36, s6
	global_load_ushort v11, v22, s[86:87]
	global_load_ushort v12, v22, s[66:67]
	s_and_b64 s[66:67], s[60:61], exec
	s_cselect_b32 s33, s33, s36
	s_add_i32 s66, s33, s5
	s_ashr_i32 s67, s66, 31
	s_mul_i32 s63, s66, 0x1c00
	s_mul_hi_i32 s36, s66, 0x1c00
	s_add_u32 s63, s79, s63
	s_addc_u32 s36, s81, s36
	s_add_u32 s86, s63, 0x800
	s_addc_u32 s87, s36, 0
	s_cmp_gt_i32 s33, 0
	s_cselect_b32 s63, 0xffffe400, 0
	s_cselect_b32 s36, -1, 0
	s_add_u32 s90, s86, s63
	s_addc_u32 s91, s87, s36
	s_cmp_lt_i32 s33, s4
	s_cselect_b32 s33, 0x1c00, 0
	s_add_u32 vcc_lo, s86, s33
	s_addc_u32 vcc_hi, s87, 0
	s_lshl_b64 s[66:67], s[66:67], 11
	s_add_u32 s33, s34, s66
	s_addc_u32 s36, s35, s67
	global_load_ushort v13, v22, s[90:91] offset:-2048
	global_load_ushort v14, v22, s[90:91]
	global_load_ushort v17, v22, s[90:91] offset:2048
	global_load_ushort v15, v22, s[86:87] offset:-2048
	global_load_ushort v75, v22, s[86:87]
	global_load_ushort v77, v22, s[86:87] offset:2048
	global_load_ushort v16, v22, vcc offset:-2048
	global_load_ushort v76, v22, vcc
	global_load_ushort v78, v22, vcc offset:2048
	s_add_u32 s86, s33, s95
	s_addc_u32 s87, s36, 0
	s_add_u32 s33, s37, s66
	s_addc_u32 s36, s39, s67
	s_add_u32 s66, s33, s95
	s_addc_u32 s67, s36, 0
	s_xor_b32 s36, s7, -3
	s_or_b32 s33, s7, 2
	s_add_i32 s36, s36, s6
	global_load_ushort v79, v22, s[86:87]
	global_load_ushort v82, v22, s[66:67]
	s_and_b64 s[66:67], s[60:61], exec
	s_cselect_b32 s33, s33, s36
	s_add_i32 s66, s33, s5
	s_ashr_i32 s67, s66, 31
	s_mul_i32 s63, s66, 0x1c00
	s_mul_hi_i32 s36, s66, 0x1c00
	s_add_u32 s63, s79, s63
	s_addc_u32 s36, s81, s36
	s_add_u32 s86, s63, 0x800
	s_addc_u32 s87, s36, 0
	s_cmp_gt_i32 s33, 0
	s_cselect_b32 s63, 0xffffe400, 0
	s_cselect_b32 s36, -1, 0
	s_add_u32 s90, s86, s63
	s_addc_u32 s91, s87, s36
	s_cmp_lt_i32 s33, s4
	s_cselect_b32 s33, 0x1c00, 0
	s_add_u32 vcc_lo, s86, s33
	s_addc_u32 vcc_hi, s87, 0
	s_lshl_b64 s[66:67], s[66:67], 11
	s_add_u32 s33, s34, s66
	s_addc_u32 s36, s35, s67
	global_load_ushort v83, v22, s[90:91] offset:-2048
	global_load_ushort v98, v22, s[90:91]
	global_load_ushort v99, v22, s[90:91] offset:2048
	global_load_ushort v100, v22, s[86:87] offset:-2048
	global_load_ushort v102, v22, s[86:87]
	global_load_ushort v104, v22, s[86:87] offset:2048
	global_load_ushort v101, v22, vcc offset:-2048
	global_load_ushort v103, v22, vcc
	global_load_ushort v105, v22, vcc offset:2048
	s_add_u32 s86, s33, s95
	s_addc_u32 s87, s36, 0
	s_add_u32 s33, s37, s66
	s_addc_u32 s36, s39, s67
	s_add_u32 s66, s33, s95
	s_addc_u32 s67, s36, 0
	s_or_b32 s33, s7, 3
	s_xor_b32 s7, s7, -4
	s_add_i32 s36, s7, s6
	s_and_b64 s[6:7], s[60:61], exec
	s_cselect_b32 s33, s33, s36
	s_add_i32 s6, s33, s5
	s_ashr_i32 s7, s6, 31
	s_mul_i32 s36, s6, 0x1c00
	s_mul_hi_i32 s5, s6, 0x1c00
	s_add_u32 s36, s79, s36
	s_addc_u32 s5, s81, s5
	global_load_ushort v106, v22, s[86:87]
	global_load_ushort v107, v22, s[66:67]
	s_add_u32 s66, s36, 0x800
	s_addc_u32 s67, s5, 0
	s_cmp_gt_i32 s33, 0
	s_cselect_b32 s36, 0xffffe400, 0
	s_cselect_b32 s5, -1, 0
	s_add_u32 s86, s66, s36
	s_addc_u32 s87, s67, s5
	s_cmp_lt_i32 s33, s4
	s_cselect_b32 s4, 0x1c00, 0
	s_add_u32 s4, s66, s4
	s_addc_u32 s5, s67, 0
	global_load_ushort v108, v22, s[86:87] offset:-2048
	global_load_ushort v110, v22, s[86:87]
	global_load_ushort v113, v22, s[86:87] offset:2048
	global_load_ushort v109, v22, s[66:67] offset:-2048
	global_load_ushort v111, v22, s[66:67]
	global_load_ushort v114, v22, s[66:67] offset:2048
	global_load_ushort v112, v22, s[4:5] offset:-2048
	global_load_ushort v115, v22, s[4:5]
	global_load_ushort v116, v22, s[4:5] offset:2048
	s_lshl_b64 s[4:5], s[6:7], 11
	s_add_u32 s6, s34, s4
	s_addc_u32 s7, s35, s5
	s_add_u32 s6, s6, s95
	s_addc_u32 s7, s7, 0
	s_add_u32 s4, s37, s4
	s_addc_u32 s5, s39, s5
	s_add_u32 s4, s4, s95
	s_addc_u32 s5, s5, 0
	global_load_ushort v117, v22, s[6:7]
	global_load_ushort v118, v22, s[4:5]
	s_movk_i32 s90, 0x800
	s_branch .LBB0_306
.Lsc_lastmovs:
	v_mov_b32_e32 v2, v69
	v_mov_b32_e32 v3, v71
	v_mov_b32_e32 v6, v72
	v_mov_b32_e32 v4, v66
	v_mov_b32_e32 v5, v70
	v_mov_b32_e32 v9, v67
	v_mov_b32_e32 v7, v56
	v_mov_b32_e32 v8, v68
	v_mov_b32_e32 v10, v65
	v_mov_b32_e32 v11, v39
	v_mov_b32_e32 v12, v51
	v_mov_b32_e32 v13, v52
	v_mov_b32_e32 v15, v64
	v_mov_b32_e32 v16, v62
	v_mov_b32_e32 v14, v44
	v_mov_b32_e32 v75, v61
	v_mov_b32_e32 v76, v47
	v_mov_b32_e32 v17, v35
	v_mov_b32_e32 v77, v55
	v_mov_b32_e32 v78, v40
	v_mov_b32_e32 v79, v27
	v_mov_b32_e32 v82, v34
	v_mov_b32_e32 v83, v30
	v_mov_b32_e32 v100, v63
	v_mov_b32_e32 v101, v59
	v_mov_b32_e32 v98, v25
	v_mov_b32_e32 v102, v57
	v_mov_b32_e32 v103, v45
	v_mov_b32_e32 v99, v23
	v_mov_b32_e32 v104, v53
	v_mov_b32_e32 v105, v37
	v_mov_b32_e32 v106, v41
	v_mov_b32_e32 v107, v49
	v_mov_b32_e32 v108, v50
	v_mov_b32_e32 v109, v58
	v_mov_b32_e32 v112, v60
	v_mov_b32_e32 v110, v42
	v_mov_b32_e32 v111, v54
	v_mov_b32_e32 v115, v46
	v_mov_b32_e32 v113, v32
	v_mov_b32_e32 v114, v48
	v_mov_b32_e32 v116, v38
	v_mov_b32_e32 v117, v26
	v_mov_b32_e32 v118, v43
	s_branch .LBB0_306
